# prologue H=modulate(x) row loop: four chunk loads per row issued together plus next-row prefetch (was load-wait-store per chunk)
# baseline (speedup 1.0000x reference)
; DI void phase_prologue_b(const Params& p, int bid, int nb) {
;     ...
;   for (int u = bid; u < 512 + 192; u += nb) {
;     if (u < 512) {
;       const int row0 = u * 64, b = row0 >> 12;
;       f32x4 sh[4], sc[4];
; #pragma unroll
;       for (int e = 0; e < 4; ++e) { const int col = e * 256 + lane * 4;
;         f32x4 a = *(const f32x4*)(p.b_ada + col), c = *(const f32x4*)(p.b_ada + 1024 + col);
;         for (int kc = 0; kc < 8; ++kc) { const float* mp = p.modp + ((size_t)(kc * 2 + 0) * 8 + b) * 6144; a += *(const f32x4*)(mp + col); c += *(const f32x4*)(mp + 1024 + col); }
;         sh[e] = a; sc[e] = c + 1.f; }
.LBB0_95:
	s_and_saveexec_b64 s[2:3], s[0:1]
	s_cbranch_execz .LBB0_90
	s_ashr_i32 s4, s62, 6
	v_readlane_b32 s8, v252, 17
	s_mul_hi_i32 s5, s4, 0x6000
	s_mulk_i32 s4, 0x6000
	v_readlane_b32 s14, v252, 23
	v_readlane_b32 s15, v252, 24
	s_add_u32 s4, s14, s4
	s_addc_u32 s5, s15, s5
	global_load_dwordx4 v[0:3], v[4:5], off
	global_load_dwordx4 v[20:23], v[6:7], off
	global_load_dwordx4 v[24:27], v54, s[4:5]
	s_add_u32 s6, s4, 0x1000
	s_addc_u32 s7, s5, 0
	v_readlane_b32 s9, v252, 18
	s_add_u32 s8, s4, 0x60000
	s_addc_u32 s9, s5, 0
	v_readlane_b32 s10, v252, 19
	v_readlane_b32 s11, v252, 20
	s_add_u32 s10, s4, 0x61000
	s_addc_u32 s11, s5, 0
	v_readlane_b32 s12, v252, 21
	v_readlane_b32 s13, v252, 22
	s_add_u32 s12, s4, 0xc0000
	s_addc_u32 s13, s5, 0
	s_add_u32 s14, s4, 0xc1000
	s_addc_u32 s15, s5, 0
	s_add_u32 s34, s4, 0x120000
	s_addc_u32 s35, s5, 0
	s_add_u32 s44, s4, 0x121000
	s_addc_u32 s45, s5, 0
	s_add_u32 s46, s4, 0x180000
	s_addc_u32 s47, s5, 0
	s_add_u32 s48, s4, 0x181000
	s_addc_u32 s49, s5, 0
	s_add_u32 s50, s4, 0x1e0000
	s_addc_u32 s51, s5, 0
	s_add_u32 s52, s4, 0x1e1000
	s_addc_u32 s53, s5, 0
	s_add_u32 s54, s4, 0x240000
	s_addc_u32 s55, s5, 0
	s_add_u32 s56, s4, 0x241000
	s_addc_u32 s57, s5, 0
	s_add_u32 s58, s4, 0x2a0000
	s_addc_u32 s59, s5, 0
	s_add_u32 s60, s4, 0x2a1000
	s_addc_u32 s61, s5, 0
	v_ashrrev_i32_e32 v17, 31, v16
	v_readlane_b32 s16, v252, 25
	v_readlane_b32 s17, v252, 26
	v_readlane_b32 s18, v252, 27
	v_readlane_b32 s19, v252, 28
	v_readlane_b32 s20, v252, 29
	v_readlane_b32 s21, v252, 30
	v_readlane_b32 s22, v252, 31
	v_readlane_b32 s23, v252, 32
	global_load_dwordx4 v[64:67], v54, s[6:7]
	global_load_dwordx4 v[68:71], v54, s[8:9]
	global_load_dwordx4 v[72:75], v54, s[10:11]
	global_load_dwordx4 v[76:79], v54, s[12:13]
	global_load_dwordx4 v[80:83], v54, s[14:15]
	global_load_dwordx4 v[84:87], v54, s[34:35]
	global_load_dwordx4 v[88:91], v54, s[44:45]
	global_load_dwordx4 v[92:95], v54, s[46:47]
	global_load_dwordx4 v[96:99], v54, s[48:49]
	global_load_dwordx4 v[100:103], v54, s[50:51]
	global_load_dwordx4 v[104:107], v54, s[52:53]
	global_load_dwordx4 v[108:111], v54, s[54:55]
	global_load_dwordx4 v[112:115], v54, s[56:57]
	global_load_dwordx4 v[116:119], v54, s[58:59]
	global_load_dwordx4 v[120:123], v54, s[60:61]
	s_waitcnt vmcnt(0)
	v_pk_add_f32 v[26:27], v[2:3], v[26:27]
	v_pk_add_f32 v[24:25], v[0:1], v[24:25]
	v_pk_add_f32 v[22:23], v[22:23], v[66:67]
	v_pk_add_f32 v[20:21], v[20:21], v[64:65]
	v_pk_add_f32 v[26:27], v[26:27], v[70:71]
	v_pk_add_f32 v[24:25], v[24:25], v[68:69]
	v_pk_add_f32 v[22:23], v[22:23], v[74:75]
	v_pk_add_f32 v[20:21], v[20:21], v[72:73]
	v_pk_add_f32 v[26:27], v[26:27], v[78:79]
	v_pk_add_f32 v[24:25], v[24:25], v[76:77]
	v_pk_add_f32 v[22:23], v[22:23], v[82:83]
	v_pk_add_f32 v[20:21], v[20:21], v[80:81]
	v_pk_add_f32 v[26:27], v[26:27], v[86:87]
	v_pk_add_f32 v[24:25], v[24:25], v[84:85]
	v_pk_add_f32 v[22:23], v[22:23], v[90:91]
	v_pk_add_f32 v[20:21], v[20:21], v[88:89]
	v_pk_add_f32 v[26:27], v[26:27], v[94:95]
	v_pk_add_f32 v[24:25], v[24:25], v[92:93]
	v_pk_add_f32 v[22:23], v[22:23], v[98:99]
	v_pk_add_f32 v[20:21], v[20:21], v[96:97]
	v_pk_add_f32 v[26:27], v[26:27], v[102:103]
	v_pk_add_f32 v[24:25], v[24:25], v[100:101]
	v_pk_add_f32 v[22:23], v[22:23], v[106:107]
	v_pk_add_f32 v[20:21], v[20:21], v[104:105]
	v_pk_add_f32 v[26:27], v[26:27], v[110:111]
	v_pk_add_f32 v[24:25], v[24:25], v[108:109]
	v_pk_add_f32 v[28:29], v[22:23], v[114:115]
	v_pk_add_f32 v[30:31], v[20:21], v[112:113]
	v_pk_add_f32 v[20:21], v[26:27], v[118:119]
	v_pk_add_f32 v[22:23], v[24:25], v[116:117]
	v_pk_add_f32 v[2:3], v[28:29], v[122:123]
	v_pk_add_f32 v[0:1], v[30:31], v[120:121]
	v_pk_add_f32 v[24:25], v[2:3], 1.0 op_sel_hi:[1,0]
	v_pk_add_f32 v[26:27], v[0:1], 1.0 op_sel_hi:[1,0]
	global_load_dwordx4 v[0:3], v[4:5], off offset:1024
	global_load_dwordx4 v[28:31], v[8:9], off
	global_load_dwordx4 v[32:35], v54, s[4:5] offset:1024
	global_load_dwordx4 v[64:67], v55, s[6:7]
	global_load_dwordx4 v[68:71], v55, s[8:9]
	global_load_dwordx4 v[72:75], v55, s[10:11]
	global_load_dwordx4 v[76:79], v55, s[12:13]
	global_load_dwordx4 v[80:83], v55, s[14:15]
	global_load_dwordx4 v[84:87], v55, s[34:35]
	global_load_dwordx4 v[88:91], v55, s[44:45]
	global_load_dwordx4 v[92:95], v55, s[46:47]
	global_load_dwordx4 v[96:99], v55, s[48:49]
	global_load_dwordx4 v[100:103], v55, s[50:51]
	global_load_dwordx4 v[104:107], v55, s[52:53]
	global_load_dwordx4 v[108:111], v55, s[54:55]
	global_load_dwordx4 v[112:115], v55, s[56:57]
	global_load_dwordx4 v[116:119], v55, s[58:59]
	global_load_dwordx4 v[120:123], v55, s[60:61]
	s_waitcnt vmcnt(0)
; DI void st4(bf16_t* p, float a, float b, float c, float d) { u32x2 w = {pk2(a, b), pk2(c, d)}; *(u32x2*)p = w; }
; DI void phase_prologue_b(const Params& p, int bid, int nb) {
;     ...
;       for (int e = 0; e < 4; ++e) { const int col = e * 256 + lane * 4;
;         f32x4 a = *(const f32x4*)(p.b_ada + col), c = *(const f32x4*)(p.b_ada + 1024 + col);
;         for (int kc = 0; kc < 8; ++kc) { const float* mp = p.modp + ((size_t)(kc * 2 + 0) * 8 + b) * 6144; a += *(const f32x4*)(mp + col); c += *(const f32x4*)(mp + 1024 + col); }
;         sh[e] = a; sc[e] = c + 1.f; }
;       for (int r = wid; r < 64; r += 8) { const size_t row = (size_t)(row0 + r);
; #pragma unroll
;         for (int e = 0; e < 4; ++e) { const int col = e * 256 + lane * 4; const f32x4 xv = *(const f32x4*)(p.x + row * DM + col); const f32x4 hv = xv * sc[e] + sh[e];
;           st4(p.H + row * DM + col, hv[0], hv[1], hv[2], hv[3]); } }
	v_pk_add_f32 v[34:35], v[2:3], v[34:35]
	v_pk_add_f32 v[32:33], v[0:1], v[32:33]
	v_pk_add_f32 v[30:31], v[30:31], v[66:67]
	v_pk_add_f32 v[28:29], v[28:29], v[64:65]
	v_pk_add_f32 v[34:35], v[34:35], v[70:71]
	v_pk_add_f32 v[32:33], v[32:33], v[68:69]
	v_pk_add_f32 v[30:31], v[30:31], v[74:75]
	v_pk_add_f32 v[28:29], v[28:29], v[72:73]
	v_pk_add_f32 v[34:35], v[34:35], v[78:79]
	v_pk_add_f32 v[32:33], v[32:33], v[76:77]
	v_pk_add_f32 v[30:31], v[30:31], v[82:83]
	v_pk_add_f32 v[28:29], v[28:29], v[80:81]
	v_pk_add_f32 v[34:35], v[34:35], v[86:87]
	v_pk_add_f32 v[32:33], v[32:33], v[84:85]
	v_pk_add_f32 v[30:31], v[30:31], v[90:91]
	v_pk_add_f32 v[28:29], v[28:29], v[88:89]
	v_pk_add_f32 v[34:35], v[34:35], v[94:95]
	v_pk_add_f32 v[32:33], v[32:33], v[92:93]
	v_pk_add_f32 v[30:31], v[30:31], v[98:99]
	v_pk_add_f32 v[28:29], v[28:29], v[96:97]
	v_pk_add_f32 v[34:35], v[34:35], v[102:103]
	v_pk_add_f32 v[32:33], v[32:33], v[100:101]
	v_pk_add_f32 v[30:31], v[30:31], v[106:107]
	v_pk_add_f32 v[28:29], v[28:29], v[104:105]
	v_pk_add_f32 v[34:35], v[34:35], v[110:111]
	v_pk_add_f32 v[32:33], v[32:33], v[108:109]
	v_pk_add_f32 v[36:37], v[30:31], v[114:115]
	v_pk_add_f32 v[38:39], v[28:29], v[112:113]
	v_pk_add_f32 v[28:29], v[34:35], v[118:119]
	v_pk_add_f32 v[30:31], v[32:33], v[116:117]
	v_pk_add_f32 v[2:3], v[36:37], v[122:123]
	v_pk_add_f32 v[0:1], v[38:39], v[120:121]
	v_pk_add_f32 v[32:33], v[2:3], 1.0 op_sel_hi:[1,0]
	v_pk_add_f32 v[34:35], v[0:1], 1.0 op_sel_hi:[1,0]
	global_load_dwordx4 v[0:3], v[4:5], off offset:2048
	global_load_dwordx4 v[36:39], v[10:11], off
	global_load_dwordx4 v[40:43], v54, s[4:5] offset:2048
	global_load_dwordx4 v[64:67], v56, s[6:7]
	global_load_dwordx4 v[68:71], v56, s[8:9]
	global_load_dwordx4 v[72:75], v56, s[10:11]
	global_load_dwordx4 v[76:79], v56, s[12:13]
	global_load_dwordx4 v[80:83], v56, s[14:15]
	global_load_dwordx4 v[84:87], v56, s[34:35]
	global_load_dwordx4 v[88:91], v56, s[44:45]
	global_load_dwordx4 v[92:95], v56, s[46:47]
	global_load_dwordx4 v[96:99], v56, s[48:49]
	global_load_dwordx4 v[100:103], v56, s[50:51]
	global_load_dwordx4 v[104:107], v56, s[52:53]
	global_load_dwordx4 v[108:111], v56, s[54:55]
	global_load_dwordx4 v[112:115], v56, s[56:57]
	global_load_dwordx4 v[116:119], v56, s[58:59]
	global_load_dwordx4 v[120:123], v56, s[60:61]
	s_waitcnt vmcnt(0)
	v_pk_add_f32 v[42:43], v[2:3], v[42:43]
	v_pk_add_f32 v[40:41], v[0:1], v[40:41]
	v_pk_add_f32 v[38:39], v[38:39], v[66:67]
	v_pk_add_f32 v[36:37], v[36:37], v[64:65]
	v_pk_add_f32 v[42:43], v[42:43], v[70:71]
	v_pk_add_f32 v[40:41], v[40:41], v[68:69]
	v_pk_add_f32 v[38:39], v[38:39], v[74:75]
	v_pk_add_f32 v[36:37], v[36:37], v[72:73]
	v_pk_add_f32 v[42:43], v[42:43], v[78:79]
	v_pk_add_f32 v[40:41], v[40:41], v[76:77]
	v_pk_add_f32 v[38:39], v[38:39], v[82:83]
	v_pk_add_f32 v[36:37], v[36:37], v[80:81]
	v_pk_add_f32 v[42:43], v[42:43], v[86:87]
	v_pk_add_f32 v[40:41], v[40:41], v[84:85]
	v_pk_add_f32 v[38:39], v[38:39], v[90:91]
	v_pk_add_f32 v[36:37], v[36:37], v[88:89]
	v_pk_add_f32 v[42:43], v[42:43], v[94:95]
	v_pk_add_f32 v[40:41], v[40:41], v[92:93]
	v_pk_add_f32 v[38:39], v[38:39], v[98:99]
	v_pk_add_f32 v[36:37], v[36:37], v[96:97]
	v_pk_add_f32 v[42:43], v[42:43], v[102:103]
	v_pk_add_f32 v[40:41], v[40:41], v[100:101]
	v_pk_add_f32 v[38:39], v[38:39], v[106:107]
	v_pk_add_f32 v[36:37], v[36:37], v[104:105]
	v_pk_add_f32 v[42:43], v[42:43], v[110:111]
	v_pk_add_f32 v[40:41], v[40:41], v[108:109]
	v_pk_add_f32 v[44:45], v[38:39], v[114:115]
	v_pk_add_f32 v[46:47], v[36:37], v[112:113]
	v_pk_add_f32 v[36:37], v[42:43], v[118:119]
	v_pk_add_f32 v[38:39], v[40:41], v[116:117]
	v_pk_add_f32 v[2:3], v[44:45], v[122:123]
	v_pk_add_f32 v[0:1], v[46:47], v[120:121]
	v_pk_add_f32 v[40:41], v[2:3], 1.0 op_sel_hi:[1,0]
	v_pk_add_f32 v[42:43], v[0:1], 1.0 op_sel_hi:[1,0]
	global_load_dwordx4 v[0:3], v[4:5], off offset:3072
	global_load_dwordx4 v[44:47], v[12:13], off
	global_load_dwordx4 v[48:51], v54, s[4:5] offset:3072
	s_mov_b64 s[4:5], 0
	global_load_dwordx4 v[64:67], v57, s[6:7]
	global_load_dwordx4 v[68:71], v57, s[8:9]
	global_load_dwordx4 v[72:75], v57, s[10:11]
	global_load_dwordx4 v[76:79], v57, s[12:13]
	global_load_dwordx4 v[80:83], v57, s[14:15]
	global_load_dwordx4 v[84:87], v57, s[34:35]
	global_load_dwordx4 v[88:91], v57, s[44:45]
	global_load_dwordx4 v[92:95], v57, s[46:47]
	global_load_dwordx4 v[96:99], v57, s[48:49]
	global_load_dwordx4 v[100:103], v57, s[50:51]
	global_load_dwordx4 v[104:107], v57, s[52:53]
	global_load_dwordx4 v[108:111], v57, s[54:55]
	global_load_dwordx4 v[112:115], v57, s[56:57]
	global_load_dwordx4 v[116:119], v57, s[58:59]
	global_load_dwordx4 v[120:123], v57, s[60:61]
	s_waitcnt vmcnt(0)
	v_pk_add_f32 v[50:51], v[2:3], v[50:51]
	v_pk_add_f32 v[48:49], v[0:1], v[48:49]
	v_pk_add_f32 v[46:47], v[46:47], v[66:67]
	v_pk_add_f32 v[44:45], v[44:45], v[64:65]
	v_pk_add_f32 v[50:51], v[50:51], v[70:71]
	v_pk_add_f32 v[48:49], v[48:49], v[68:69]
	v_pk_add_f32 v[46:47], v[46:47], v[74:75]
	v_pk_add_f32 v[44:45], v[44:45], v[72:73]
	v_pk_add_f32 v[50:51], v[50:51], v[78:79]
	v_pk_add_f32 v[48:49], v[48:49], v[76:77]
	v_pk_add_f32 v[46:47], v[46:47], v[82:83]
	v_pk_add_f32 v[44:45], v[44:45], v[80:81]
	v_pk_add_f32 v[50:51], v[50:51], v[86:87]
	v_pk_add_f32 v[48:49], v[48:49], v[84:85]
	v_pk_add_f32 v[46:47], v[46:47], v[90:91]
	v_pk_add_f32 v[44:45], v[44:45], v[88:89]
	v_pk_add_f32 v[50:51], v[50:51], v[94:95]
	v_pk_add_f32 v[48:49], v[48:49], v[92:93]
	v_pk_add_f32 v[46:47], v[46:47], v[98:99]
	v_pk_add_f32 v[44:45], v[44:45], v[96:97]
	v_pk_add_f32 v[50:51], v[50:51], v[102:103]
	v_pk_add_f32 v[48:49], v[48:49], v[100:101]
	v_pk_add_f32 v[46:47], v[46:47], v[106:107]
	v_pk_add_f32 v[44:45], v[44:45], v[104:105]
	v_pk_add_f32 v[58:59], v[50:51], v[110:111]
	v_pk_add_f32 v[60:61], v[48:49], v[108:109]
	v_pk_add_f32 v[48:49], v[46:47], v[114:115]
	v_pk_add_f32 v[50:51], v[44:45], v[112:113]
	v_pk_add_f32 v[44:45], v[58:59], v[118:119]
	v_pk_add_f32 v[46:47], v[60:61], v[116:117]
	v_pk_add_f32 v[2:3], v[48:49], v[122:123]
	v_pk_add_f32 v[48:49], v[50:51], v[120:121]
	v_pk_add_f32 v[0:1], v[2:3], 1.0 op_sel_hi:[1,0]
	v_pk_add_f32 v[2:3], v[48:49], 1.0 op_sel_hi:[1,0]
	v_lshlrev_b64 v[48:49], 12, v[16:17]
	v_lshlrev_b64 v[50:51], 11, v[16:17]
	v_lshl_add_u64 v[48:49], v[14:15], 0, v[48:49]
	v_lshl_add_u64 v[50:51], v[18:19], 0, v[50:51]
	v_mov_b32_e32 v17, v53
	global_load_dwordx4 v[80:83], v[48:49], off offset:-2048
	global_load_dwordx4 v[84:87], v[48:49], off offset:-1024
	global_load_dwordx4 v[88:91], v[48:49], off
	global_load_dwordx4 v[92:95], v[48:49], off offset:1024
	s_waitcnt vmcnt(0)
; DI void st4(bf16_t* p, float a, float b, float c, float d) { u32x2 w = {pk2(a, b), pk2(c, d)}; *(u32x2*)p = w; }
; DI void phase_prologue_b(const Params& p, int bid, int nb) {
;     ...
;       for (int r = wid; r < 64; r += 8) { const size_t row = (size_t)(row0 + r);
; #pragma unroll
;         for (int e = 0; e < 4; ++e) { const int col = e * 256 + lane * 4; const f32x4 xv = *(const f32x4*)(p.x + row * DM + col); const f32x4 hv = xv * sc[e] + sh[e];
;           st4(p.H + row * DM + col, hv[0], hv[1], hv[2], hv[3]); } }
.LBB0_97:
	s_waitcnt vmcnt(4)
	v_mov_b64_e32 v[64:65], v[80:81]
	v_mov_b64_e32 v[66:67], v[82:83]
	v_mov_b64_e32 v[68:69], v[84:85]
	v_mov_b64_e32 v[70:71], v[86:87]
	v_mov_b64_e32 v[72:73], v[88:89]
	v_mov_b64_e32 v[74:75], v[90:91]
	v_mov_b64_e32 v[76:77], v[92:93]
	v_mov_b64_e32 v[78:79], v[94:95]
	v_add_u32_e32 v17, 8, v17
	s_mov_b64 s[6:7], 0x8000
	s_mov_b64 s[8:9], 0x4000
	v_cmp_lt_i32_e32 vcc, 55, v17
	s_or_b64 s[4:5], vcc, s[4:5]
	v_lshl_add_u64 v[96:97], v[48:49], 0, s[6:7]
	s_nop 0
	v_cndmask_b32_e32 v96, v96, v48, vcc
	v_cndmask_b32_e32 v97, v97, v49, vcc
	global_load_dwordx4 v[80:83], v[96:97], off offset:-2048
	global_load_dwordx4 v[84:87], v[96:97], off offset:-1024
	global_load_dwordx4 v[88:91], v[96:97], off
	global_load_dwordx4 v[92:95], v[96:97], off offset:1024
	v_pk_fma_f32 v[66:67], v[24:25], v[66:67], v[20:21]
	v_pk_fma_f32 v[64:65], v[26:27], v[64:65], v[22:23]
	s_nop 0
	v_cvt_pk_bf16_f32 v64, v64, v65
	v_cvt_pk_bf16_f32 v65, v66, v67
	global_store_dwordx2 v[50:51], v[64:65], off offset:-1024
	v_pk_fma_f32 v[70:71], v[32:33], v[70:71], v[28:29]
	v_pk_fma_f32 v[68:69], v[34:35], v[68:69], v[30:31]
	s_nop 0
	v_cvt_pk_bf16_f32 v68, v68, v69
	v_cvt_pk_bf16_f32 v69, v70, v71
	global_store_dwordx2 v[50:51], v[68:69], off offset:-512
	v_pk_fma_f32 v[74:75], v[40:41], v[74:75], v[36:37]
	v_pk_fma_f32 v[72:73], v[42:43], v[72:73], v[38:39]
	s_nop 0
	v_cvt_pk_bf16_f32 v72, v72, v73
	v_cvt_pk_bf16_f32 v73, v74, v75
	global_store_dwordx2 v[50:51], v[72:73], off
	v_pk_fma_f32 v[78:79], v[0:1], v[78:79], v[44:45]
	v_pk_fma_f32 v[76:77], v[2:3], v[76:77], v[46:47]
	s_nop 0
	v_cvt_pk_bf16_f32 v76, v76, v77
	v_cvt_pk_bf16_f32 v77, v78, v79
	global_store_dwordx2 v[50:51], v[76:77], off offset:512
	v_lshl_add_u64 v[48:49], v[48:49], 0, s[6:7]
	v_lshl_add_u64 v[50:51], v[50:51], 0, s[8:9]
	s_andn2_b64 exec, exec, s[4:5]
	s_cbranch_execnz .LBB0_97
	s_branch .LBB0_90
